# steal rebalance v5: ph20's idle tail now converts FFN3 down (reusing the ph13 loop with its own zeroed counter); conversions re-spread so ph3 and ph6 tails carry less
# speedup vs baseline: 1.0063x; 1.0018x over previous
; __device__ __forceinline__ void convert_item(const Args& a, int it, LAS float* scr, int lane) {
;     ...
;         if (it < T_FFN) { const int m = it / 2752, r = it % 2752, f = m / 3, kind = m % 3;
;             if (kind < 2) { k0 = (r / 86) * 64; n0 = (r % 86) * 64; src = a.in[kind ? I_WU : I_WG] + (size_t)f * DM * DFF; ldn = DFF; Kd = DM; dst = WGU + (size_t)f * 2 * DFF * DM; drow = (n0 >> 7) * 256 + kind * 128 + (n0 & 127); }
;             else { k0 = (r / 32) * 64; n0 = (r % 32) * 64; src = a.in[I_WDN] + (size_t)f * DFF * DM; ldn = DM; Kd = DFF; dst = WD + (size_t)f * DM * DFF; drow = n0; }
;     ...
;     for (;;) {
;         __syncthreads();
;         if (tid == 0) bc[0] = (int)__hip_atomic_fetch_add(ctr, (unsigned)NSTEAL, __ATOMIC_RELAXED, __HIP_MEMORY_SCOPE_AGENT);
;         __syncthreads();
;         const int base = bc[0];
;         if (base >= n) break;
;         const int j = base + w;
;         if (w < NSTEAL && j < n) convert_item(a, j < n1 ? lo1 + j : (j < n1 + n2 ? lo2 + (j - n1) : lo3 + (j - n1 - n2)), scr, lane);
.LBB0_214:
	s_or_b64 exec, exec, s[8:9]
	v_mov_b32_e32 v1, s23
	s_waitcnt lgkmcnt(0)
	s_barrier
	ds_read_b32 v1, v1
	s_movk_i32 s8, 0x203f
	s_waitcnt lgkmcnt(0)
	v_cmp_lt_i32_e32 vcc, s8, v1
	v_readfirstlane_b32 s10, v1
	s_mov_b64 s[8:9], -1
	s_cbranch_vccnz .LBB0_209
	s_add_i32 s8, s10, s4
	s_cmpk_lt_i32 s8, 0x2040
	s_cselect_b64 s[10:11], -1, 0
	s_and_b64 s[10:11], s[6:7], s[10:11]
	s_andn2_b64 vcc, exec, s[10:11]
	s_cbranch_vccnz .LBB0_208
	s_cmpk_lt_i32 s8, 0x1580
	s_movk_i32 s9, 0x2b00
	s_cselect_b32 s9, s9, 0x2b00
	s_add_i32 s9, s9, s8
	s_mul_hi_i32 s8, s9, 0x2fa0be83
	s_lshr_b32 s10, s8, 31
	s_ashr_i32 s8, s8, 9
	s_add_i32 s8, s8, s10
	s_mul_i32 s10, s8, 0xac0
	s_sub_i32 s14, s9, s10
	s_mul_hi_i32 s9, s9, 0xfe03f81
	s_lshr_b32 s10, s9, 31
	s_ashr_i32 s26, s9, 9
	s_mul_hi_i32 s9, s8, 0x55555556
	s_add_i32 s26, s26, s10
	s_lshr_b32 s10, s9, 31
	s_add_i32 s9, s9, s10
	s_mul_i32 s9, s9, 3
	s_sub_i32 s13, s8, s9
	s_cmp_gt_i32 s13, 1
	s_mov_b64 s[8:9], -1
	s_sext_i32_i16 s18, s14
	s_mul_hi_i32 s15, s26, 0x2b00000
	s_mul_i32 s19, s26, 0x2b00000
	s_cbranch_scc0 .LBB0_218
	s_bfe_u32 s8, s18, 0x5001a
	s_add_i32 s8, s14, s8
	s_sext_i32_i16 s9, s8
	s_and_b32 s8, s8, 0xffe0
	s_sub_i32 s8, s14, s8
	s_sext_i32_i16 s8, s8
	v_readlane_b32 s64, v248, 11
	s_lshr_b32 s12, s9, 5
	s_lshl_b32 s25, s8, 6
	v_readlane_b32 s66, v248, 13
	v_readlane_b32 s67, v248, 14
	s_add_u32 s16, s66, s19
	s_addc_u32 s17, s67, s15
	s_mul_hi_i32 s8, s26, 0x1580000
	s_mul_i32 s26, s26, 0x1580000
	v_readlane_b32 s9, v248, 40
	s_add_u32 s10, s9, s26
	v_readlane_b32 s9, v248, 41
	v_readlane_b32 s65, v248, 12
	v_readlane_b32 s68, v248, 15
	v_readlane_b32 s69, v248, 16
	v_readlane_b32 s70, v248, 17
	v_readlane_b32 s71, v248, 18
	v_readlane_b32 s72, v248, 19
	v_readlane_b32 s73, v248, 20
	v_readlane_b32 s74, v248, 21
	v_readlane_b32 s75, v248, 22
	v_readlane_b32 s76, v248, 23
	v_readlane_b32 s77, v248, 24
	v_readlane_b32 s78, v248, 25
	v_readlane_b32 s79, v248, 26
	s_addc_u32 s11, s9, s8
	s_mov_b64 s[8:9], 0

; #define LAS __attribute__((address_space(3)))
; __device__ __forceinline__ int otid() { int t = threadIdx.x; asm volatile("" : "+v"(t)); return t; }
;     const int tid = otid(), w = __builtin_amdgcn_readfirstlane(tid >> 6), lane = tid & 63;
;     LAS float* scr = (LAS float*)lds + w * (64 * 65);
;     volatile LAS int* bc = (volatile LAS int*)(lds + LDS_BYTES - 32);
;     const int n = n1 + n2 + n3;
; __global__ void __launch_bounds__(512, 2) mega(Args a) {
;     ...
;             if (ph == 10) convert_steal(a, lds, ctrs + CTR_WORD(2), 9 * 2752, 2752, 0, 0);
;             else if (ph == 13) convert_steal(a, lds, ctrs + CTR_WORD(3), 10 * 2752, 2752, 0, 0);
.LBB0_443:
	v_readlane_b32 s48, v246, 54
	s_mov_b64 s[12:13], -1
	s_and_b64 vcc, exec, s[10:11]
	v_readlane_b32 s49, v246, 55
	v_readlane_b32 s50, v246, 56
	v_readlane_b32 s51, v246, 57
	v_readlane_b32 s52, v246, 58
	v_readlane_b32 s53, v246, 59
	v_readlane_b32 s54, v246, 60
	v_readlane_b32 s55, v246, 61
	v_readlane_b32 s56, v246, 62
	v_readlane_b32 s57, v246, 63
	v_readlane_b32 s58, v219, 0
	v_readlane_b32 s59, v219, 1
	v_readlane_b32 s60, v219, 2
	v_readlane_b32 s61, v219, 3
	v_readlane_b32 s62, v219, 4
	v_readlane_b32 s63, v219, 5
	s_cbranch_vccz .LBB0_461
	s_cmp_eq_u32 s86, 20
	s_cbranch_scc1 .Lsteal_ph20
	s_andn2_b64 vcc, exec, s[8:9]
	s_cbranch_vccnz .LBB0_460
.Lsteal_ph20:
	v_mov_b32_e32 v1, v169
	s_nop 0
	v_readfirstlane_b32 s4, v1
	s_ashr_i32 s4, s4, 6
	s_mul_i32 s8, s4, 0x4100
	v_cmp_eq_u32_e64 s[38:39], 0, v1
	v_lshlrev_b32_e32 v0, 2, v1
	v_bfe_u32 v2, v1, 4, 2
	v_bfe_u32 v3, v1, 3, 3
	v_lshlrev_b32_e32 v1, 3, v1
	s_add_i32 s10, s8, 0
	v_and_b32_e32 v0, 60, v0
	v_and_b32_e32 v14, 56, v1
	s_cmp_lt_i32 s4, 4
	v_lshl_add_u32 v12, v0, 2, s10
	s_waitcnt lgkmcnt(0)
	v_mul_u32_u24_e32 v13, 0x104, v2
	v_mul_u32_u24_e32 v1, 0x104, v14
	v_lshlrev_b32_e32 v4, 2, v3
	s_cselect_b64 s[8:9], -1, 0
	v_add3_u32 v4, s10, v1, v4
	v_or_b32_e32 v5, 8, v3
	v_or_b32_e32 v6, 16, v3
	v_or_b32_e32 v7, 24, v3
	v_or_b32_e32 v8, 32, v3
	v_or_b32_e32 v9, 40, v3
	v_or_b32_e32 v10, 48, v3
	v_or_b32_e32 v11, 56, v3
	v_lshlrev_b32_e32 v152, 2, v0
	v_add_u32_e32 v12, v12, v13
	v_lshlrev_b32_e32 v0, 1, v14
	s_branch .LBB0_450

;     ...
;     for (;;) {
;         __syncthreads();
;         if (tid == 0) bc[0] = (int)__hip_atomic_fetch_add(ctr, (unsigned)NSTEAL, __ATOMIC_RELAXED, __HIP_MEMORY_SCOPE_AGENT);
.LBB0_450:
	s_waitcnt vmcnt(0)
	s_barrier
	s_and_saveexec_b64 s[10:11], s[38:39]
	s_cbranch_execz .LBB0_454
	s_mov_b64 s[14:15], exec
	v_mbcnt_lo_u32_b32 v1, s14, 0
	v_mbcnt_hi_u32_b32 v1, s15, v1
	v_cmp_eq_u32_e32 vcc, 0, v1
	s_and_saveexec_b64 s[12:13], vcc
	s_cbranch_execz .LBB0_453
	s_bcnt1_i32_b64 s14, s[14:15]
	s_lshl_b32 s14, s14, 2
	v_mov_b32_e32 v13, s14
	v_readlane_b32 s14, v248, 38
	v_readlane_b32 s15, v248, 39
	s_nop 4
	s_cmp_eq_u32 s86, 20
	s_cbranch_scc1 .Lsteal20_ctr
	global_atomic_add v13, v153, v13, s[14:15] sc0
	s_branch .LBB0_453
.Lsteal20_ctr:
	global_atomic_add v13, v153, v13, s[14:15] offset:128 sc0

; __device__ __forceinline__ void convert_item(const Args& a, int it, LAS float* scr, int lane) {
;     ...
;         if (it < T_FFN) { const int m = it / 2752, r = it % 2752, f = m / 3, kind = m % 3;
;             if (kind < 2) { k0 = (r / 86) * 64; n0 = (r % 86) * 64; src = a.in[kind ? I_WU : I_WG] + (size_t)f * DM * DFF; ldn = DFF; Kd = DM; dst = WGU + (size_t)f * 2 * DFF * DM; drow = (n0 >> 7) * 256 + kind * 128 + (n0 & 127); }
;             else { k0 = (r / 32) * 64; n0 = (r % 32) * 64; src = a.in[I_WDN] + (size_t)f * DFF * DM; ldn = DM; Kd = DFF; dst = WD + (size_t)f * DM * DFF; drow = n0; }
;     ...
;         __syncthreads();
;         const int base = bc[0];
;         if (base >= n) break;
;         const int j = base + w;
;         if (w < NSTEAL && j < n) convert_item(a, j < n1 ? lo1 + j : (j < n1 + n2 ? lo2 + (j - n1) : lo3 + (j - n1 - n2)), scr, lane);
.LBB0_454:
	s_or_b64 exec, exec, s[10:11]
	v_mov_b32_e32 v1, s23
	s_waitcnt lgkmcnt(0)
	s_barrier
	ds_read_b32 v1, v1
	s_movk_i32 s10, 0x157f
	s_cmp_eq_u32 s86, 20
	s_cselect_b32 s10, 0xabf, s10
	s_waitcnt lgkmcnt(0)
	v_cmp_lt_i32_e32 vcc, s10, v1
	v_readfirstlane_b32 s12, v1
	s_mov_b64 s[10:11], -1
	s_cbranch_vccnz .LBB0_449
	s_add_i32 s10, s12, s4
	s_movk_i32 s13, 0x1580
	s_cmp_eq_u32 s86, 20
	s_cselect_b32 s13, 0xac0, s13
	s_cmp_lt_i32 s10, s13
	s_cselect_b64 s[12:13], -1, 0
	s_and_b64 s[12:13], s[8:9], s[12:13]
	s_andn2_b64 vcc, exec, s[12:13]
	s_cbranch_vccnz .LBB0_448
	s_movk_i32 s11, 0x60c0
	s_cmp_eq_u32 s86, 20
	s_cselect_b32 s11, 0x7640, s11
	s_add_i32 s10, s10, s11
	s_mul_hi_i32 s11, s10, 0x2fa0be83
	s_lshr_b32 s12, s11, 31
	s_ashr_i32 s11, s11, 9
	s_add_i32 s11, s11, s12
	s_mul_i32 s12, s11, 0xac0
	s_sub_i32 s16, s10, s12
	s_mul_hi_i32 s10, s10, 0xfe03f81
	s_lshr_b32 s12, s10, 31
	s_ashr_i32 s28, s10, 9
	s_mul_hi_i32 s10, s11, 0x55555556
	s_add_i32 s28, s28, s12
	s_lshr_b32 s12, s10, 31
	s_add_i32 s10, s10, s12
	s_mul_i32 s10, s10, 3
	s_sub_i32 s15, s11, s10
	s_cmp_gt_i32 s15, 1
	s_mov_b64 s[10:11], -1
	s_sext_i32_i16 s26, s16
	s_mul_hi_i32 s17, s28, 0x2b00000
	s_mul_i32 s27, s28, 0x2b00000
	s_cbranch_scc0 .LBB0_458
	s_bfe_u32 s10, s26, 0x5001a
	s_add_i32 s10, s16, s10
	s_sext_i32_i16 s11, s10
	s_and_b32 s10, s10, 0xffe0
	s_sub_i32 s10, s16, s10
	s_sext_i32_i16 s10, s10
	v_readlane_b32 s64, v248, 11
	s_lshr_b32 s14, s11, 5
	s_lshl_b32 s25, s10, 6
	v_readlane_b32 s66, v248, 13
	v_readlane_b32 s67, v248, 14
	s_add_u32 s18, s66, s27
	s_addc_u32 s19, s67, s17
	s_mul_hi_i32 s10, s28, 0x1580000
	s_mul_i32 s28, s28, 0x1580000
	v_readlane_b32 s11, v248, 40
	s_add_u32 s12, s11, s28
	v_readlane_b32 s11, v248, 41
	v_readlane_b32 s65, v248, 12
	v_readlane_b32 s68, v248, 15
	v_readlane_b32 s69, v248, 16
	v_readlane_b32 s70, v248, 17
	v_readlane_b32 s71, v248, 18
	v_readlane_b32 s72, v248, 19
	v_readlane_b32 s73, v248, 20
	v_readlane_b32 s74, v248, 21
	v_readlane_b32 s75, v248, 22
	v_readlane_b32 s76, v248, 23
	v_readlane_b32 s77, v248, 24
	v_readlane_b32 s78, v248, 25
	v_readlane_b32 s79, v248, 26
	s_addc_u32 s13, s11, s10
	s_mov_b64 s[10:11], 0

; __device__ __forceinline__ void convert_item(const Args& a, int it, LAS float* scr, int lane) {
;     ...
;         if (it < T_FFN) { const int m = it / 2752, r = it % 2752, f = m / 3, kind = m % 3;
;             if (kind < 2) { k0 = (r / 86) * 64; n0 = (r % 86) * 64; src = a.in[kind ? I_WU : I_WG] + (size_t)f * DM * DFF; ldn = DFF; Kd = DM; dst = WGU + (size_t)f * 2 * DFF * DM; drow = (n0 >> 7) * 256 + kind * 128 + (n0 & 127); }
;             else { k0 = (r / 32) * 64; n0 = (r % 32) * 64; src = a.in[I_WDN] + (size_t)f * DFF * DM; ldn = DM; Kd = DFF; dst = WD + (size_t)f * DM * DFF; drow = n0; }
;     ...
;         __syncthreads();
;         const int base = bc[0];
;         if (base >= n) break;
;         const int j = base + w;
;         if (w < NSTEAL && j < n) convert_item(a, j < n1 ? lo1 + j : (j < n1 + n2 ? lo2 + (j - n1) : lo3 + (j - n1 - n2)), scr, lane);
.LBB0_471:
	s_or_b64 exec, exec, s[10:11]
	v_mov_b32_e32 v1, s23
	s_waitcnt lgkmcnt(0)
	s_barrier
	ds_read_b32 v1, v1
	s_movk_i32 s10, 0x157f
	s_waitcnt lgkmcnt(0)
	v_cmp_lt_i32_e32 vcc, s10, v1
	v_readfirstlane_b32 s12, v1
	s_mov_b64 s[10:11], -1
	s_cbranch_vccnz .LBB0_466
	s_add_i32 s10, s12, s4
	s_cmpk_lt_i32 s10, 0x1580
	s_cselect_b64 s[12:13], -1, 0
	s_and_b64 s[12:13], s[8:9], s[12:13]
	s_andn2_b64 vcc, exec, s[12:13]
	s_cbranch_vccnz .LBB0_465
	s_addk_i32 s10, 0x4b40
	s_mul_hi_i32 s11, s10, 0x2fa0be83
	s_lshr_b32 s12, s11, 31
	s_ashr_i32 s11, s11, 9
	s_add_i32 s11, s11, s12
	s_mul_i32 s12, s11, 0xac0
	s_sub_i32 s16, s10, s12
	s_mul_hi_i32 s10, s10, 0xfe03f81
	s_lshr_b32 s12, s10, 31
	s_ashr_i32 s28, s10, 9
	s_mul_hi_i32 s10, s11, 0x55555556
	s_add_i32 s28, s28, s12
	s_lshr_b32 s12, s10, 31
	s_add_i32 s10, s10, s12
	s_mul_i32 s10, s10, 3
	s_sub_i32 s15, s11, s10
	s_cmp_gt_i32 s15, 1
	s_mov_b64 s[10:11], -1
	s_sext_i32_i16 s26, s16
	s_mul_hi_i32 s17, s28, 0x2b00000
	s_mul_i32 s27, s28, 0x2b00000
	s_cbranch_scc0 .LBB0_475
	s_bfe_u32 s10, s26, 0x5001a
	s_add_i32 s10, s16, s10
	s_sext_i32_i16 s11, s10
	s_and_b32 s10, s10, 0xffe0
	s_sub_i32 s10, s16, s10
	s_sext_i32_i16 s10, s10
	v_readlane_b32 s64, v248, 11
	s_lshr_b32 s14, s11, 5
	s_lshl_b32 s25, s10, 6
	v_readlane_b32 s66, v248, 13
	v_readlane_b32 s67, v248, 14
	s_add_u32 s18, s66, s27
	s_addc_u32 s19, s67, s17
	s_mul_hi_i32 s10, s28, 0x1580000
	s_mul_i32 s28, s28, 0x1580000
	v_readlane_b32 s11, v248, 40
	s_add_u32 s12, s11, s28
	v_readlane_b32 s11, v248, 41
	v_readlane_b32 s65, v248, 12
	v_readlane_b32 s68, v248, 15
	v_readlane_b32 s69, v248, 16
	v_readlane_b32 s70, v248, 17
	v_readlane_b32 s71, v248, 18
	v_readlane_b32 s72, v248, 19
	v_readlane_b32 s73, v248, 20
	v_readlane_b32 s74, v248, 21
	v_readlane_b32 s75, v248, 22
	v_readlane_b32 s76, v248, 23
	v_readlane_b32 s77, v248, 24
	v_readlane_b32 s78, v248, 25
	v_readlane_b32 s79, v248, 26
	s_addc_u32 s13, s11, s10
	s_mov_b64 s[10:11], 0
